# P3 epilogue VALU trims: paired v_cvt_pk_bf16_f32 rounding, transpose-reduce (butterfly) for the 16 row sums, per-item E*g128 factors
# speedup vs baseline: 1.0109x; 1.0045x over previous
.LBB0_590:
	v_lshl_add_u64 v[12:13], s[82:83], 0, v[8:9]
	s_mov_b32 s4, 0x100000
	v_add_co_u32_e32 v70, vcc, s4, v12
	v_lshl_add_u64 v[10:11], s[82:83], 0, v[6:7]
	s_mov_b32 s5, 0x101000
	v_addc_co_u32_e32 v71, vcc, 0, v13, vcc
	global_load_dword v3, v[10:11], off
	v_add_co_u32_e32 v102, vcc, s5, v12
	v_lshl_add_u64 v[74:75], s[82:83], 0, v[4:5]
	s_nop 0
	v_addc_co_u32_e32 v103, vcc, 0, v13, vcc
	global_load_dwordx4 v[10:13], v[102:103], off offset:-4096
	global_load_dwordx4 v[14:17], v[70:71], off offset:512
	global_load_dwordx4 v[50:53], v[70:71], off offset:32
	global_load_dwordx4 v[54:57], v[70:71], off offset:544
	global_load_dwordx4 v[58:61], v[70:71], off offset:64
	global_load_dwordx4 v[62:65], v[70:71], off offset:576
	global_load_dwordx4 v[66:69], v[70:71], off offset:96
	s_nop 0
	global_load_dwordx4 v[70:73], v[70:71], off offset:608
	s_nop 0
	global_load_dword v107, v[74:75], off
	s_nop 0
	global_load_dwordx4 v[74:77], v[102:103], off
	global_load_dwordx4 v[78:81], v[102:103], off offset:512
	global_load_dwordx4 v[82:85], v[102:103], off offset:32
	global_load_dwordx4 v[86:89], v[102:103], off offset:544
	global_load_dwordx4 v[90:93], v[102:103], off offset:64
	global_load_dwordx4 v[94:97], v[102:103], off offset:576
	global_load_dwordx4 v[98:101], v[102:103], off offset:96
	s_nop 0
	global_load_dwordx4 v[102:105], v[102:103], off offset:608
	s_add_i32 s11, s7, 1
	v_cvt_f32_u32_e32 v106, s7
	v_cvt_f32_u32_e32 v108, s11
	s_mov_b64 s[4:5], 0x2000
	v_lshl_add_u64 v[8:9], v[8:9], 0, s[4:5]
	v_mul_f32_e32 v109, v224, v106
	v_mul_f32_e32 v110, v224, v108
	v_cmp_gt_f32_e32 vcc, s0, v109
	v_cmp_gt_f32_e64 s[4:5], s0, v110
	v_lshl_add_u64 v[4:5], v[4:5], 0, s[94:95]
	v_cndmask_b32_e32 v109, 0, v220, vcc
	v_cndmask_b32_e64 v110, 0, v220, s[4:5]
	v_fmac_f32_e32 v109, v224, v106
	v_fmac_f32_e32 v110, v224, v108
	v_exp_f32_e32 v106, v109
	v_exp_f32_e32 v108, v110
	s_and_b64 s[4:5], s[4:5], exec
	s_cselect_b32 s11, 0xffffffc0, 0
	s_and_b64 s[4:5], vcc, exec
	s_cselect_b32 s4, 0xffffffc0, 0
	v_ldexp_f32 v109, v106, s4
	v_ldexp_f32 v106, v108, s11
	s_add_i32 s7, s7, -2
	v_lshl_add_u64 v[6:7], v[6:7], 0, s[94:95]
	s_cmp_eq_u32 s7, -2
	s_waitcnt vmcnt(0)
	v_mul_f32_e32 v106, v3, v106
	v_pk_fma_f32 v[10:11], v[106:107], v[10:11], v[18:19] op_sel_hi:[0,1,1]
	v_pk_fma_f32 v[14:15], v[106:107], v[14:15], v[34:35] op_sel_hi:[0,1,1]
	v_pk_fma_f32 v[12:13], v[106:107], v[12:13], v[20:21] op_sel_hi:[0,1,1]
	v_pk_fma_f32 v[16:17], v[106:107], v[16:17], v[36:37] op_sel_hi:[0,1,1]
	v_pk_fma_f32 v[22:23], v[106:107], v[50:51], v[22:23] op_sel_hi:[0,1,1]
	v_pk_fma_f32 v[38:39], v[106:107], v[54:55], v[38:39] op_sel_hi:[0,1,1]
	v_pk_fma_f32 v[24:25], v[106:107], v[52:53], v[24:25] op_sel_hi:[0,1,1]
	v_pk_fma_f32 v[40:41], v[106:107], v[56:57], v[40:41] op_sel_hi:[0,1,1]
	v_pk_fma_f32 v[26:27], v[106:107], v[58:59], v[26:27] op_sel_hi:[0,1,1]
	v_pk_fma_f32 v[42:43], v[106:107], v[62:63], v[42:43] op_sel_hi:[0,1,1]
	v_pk_fma_f32 v[28:29], v[106:107], v[60:61], v[28:29] op_sel_hi:[0,1,1]
	v_pk_fma_f32 v[44:45], v[106:107], v[64:65], v[44:45] op_sel_hi:[0,1,1]
	v_pk_fma_f32 v[30:31], v[106:107], v[66:67], v[30:31] op_sel_hi:[0,1,1]
	v_pk_fma_f32 v[46:47], v[106:107], v[70:71], v[46:47] op_sel_hi:[0,1,1]
	v_pk_fma_f32 v[32:33], v[106:107], v[68:69], v[32:33] op_sel_hi:[0,1,1]
	v_pk_fma_f32 v[48:49], v[106:107], v[72:73], v[48:49] op_sel_hi:[0,1,1]
	v_mul_f32_e32 v50, v107, v109
	v_pk_fma_f32 v[18:19], v[50:51], v[74:75], v[10:11] op_sel_hi:[0,1,1]
	v_pk_fma_f32 v[34:35], v[50:51], v[78:79], v[14:15] op_sel_hi:[0,1,1]
	v_pk_fma_f32 v[20:21], v[50:51], v[76:77], v[12:13] op_sel_hi:[0,1,1]
	v_pk_fma_f32 v[36:37], v[50:51], v[80:81], v[16:17] op_sel_hi:[0,1,1]
	v_pk_fma_f32 v[22:23], v[50:51], v[82:83], v[22:23] op_sel_hi:[0,1,1]
	v_pk_fma_f32 v[38:39], v[50:51], v[86:87], v[38:39] op_sel_hi:[0,1,1]
	v_pk_fma_f32 v[24:25], v[50:51], v[84:85], v[24:25] op_sel_hi:[0,1,1]
	v_pk_fma_f32 v[40:41], v[50:51], v[88:89], v[40:41] op_sel_hi:[0,1,1]
	v_pk_fma_f32 v[26:27], v[50:51], v[90:91], v[26:27] op_sel_hi:[0,1,1]
	v_pk_fma_f32 v[42:43], v[50:51], v[94:95], v[42:43] op_sel_hi:[0,1,1]
	v_pk_fma_f32 v[28:29], v[50:51], v[92:93], v[28:29] op_sel_hi:[0,1,1]
	v_pk_fma_f32 v[44:45], v[50:51], v[96:97], v[44:45] op_sel_hi:[0,1,1]
	v_pk_fma_f32 v[30:31], v[50:51], v[98:99], v[30:31] op_sel_hi:[0,1,1]
	v_pk_fma_f32 v[46:47], v[50:51], v[102:103], v[46:47] op_sel_hi:[0,1,1]
	v_pk_fma_f32 v[32:33], v[50:51], v[100:101], v[32:33] op_sel_hi:[0,1,1]
	v_pk_fma_f32 v[48:49], v[50:51], v[104:105], v[48:49] op_sel_hi:[0,1,1]
	s_cbranch_scc0 .LBB0_590
	s_ashr_i32 s52, s84, 5
	s_ashr_i32 s53, s52, 31
	s_lshl_b64 s[4:5], s[52:53], 12
	v_mov_b32_e32 v5, s5
	v_or_b32_e32 v4, s4, v154
	v_mov_b32_e32 v9, s5
	v_or_b32_e32 v8, s4, v156
	v_readlane_b32 s4, v255, 15
	v_lshlrev_b64 v[4:5], 11, v[4:5]
	v_readlane_b32 s5, v255, 16
	v_lshl_add_u64 v[6:7], s[86:87], 0, v[4:5]
	s_mov_b32 s7, s91
	v_lshl_add_u64 v[4:5], s[4:5], 0, v[4:5]
	v_lshlrev_b64 v[8:9], 12, v[8:9]
	v_lshl_add_u64 v[4:5], v[4:5], 0, s[6:7]
	v_mov_b32_e32 v169, v2
	s_and_b32 s11, s84, 7
	v_lshl_add_u64 v[16:17], v[4:5], 0, v[168:169]
	v_lshl_add_u64 v[4:5], s[88:89], 0, v[8:9]
	s_mov_b32 s55, s91
	v_lshl_add_u64 v[4:5], v[4:5], 0, s[54:55]
	s_lshl_b32 s4, s11, 7
	s_mov_b32 s5, s91
	v_lshl_add_u64 v[56:57], v[4:5], 0, s[4:5]
	s_mov_b32 s4, 0x10000
	v_lshl_add_u64 v[6:7], v[6:7], 0, s[6:7]
	v_add_co_u32_e32 v8, vcc, s4, v16
	v_lshl_add_u64 v[54:55], v[6:7], 0, v[168:169]
	s_nop 0
	v_addc_co_u32_e32 v9, vcc, 0, v17, vcc
	v_add_co_u32_e32 v58, vcc, s4, v54
	s_mov_b32 s4, 0x20000
	s_nop 0
	v_addc_co_u32_e32 v59, vcc, 0, v55, vcc
	v_add_co_u32_e32 v12, vcc, s4, v16
	global_load_dwordx4 v[114:117], v[16:17], off
	global_load_dwordx4 v[4:7], v[54:55], off
	v_addc_co_u32_e32 v13, vcc, 0, v17, vcc
	v_add_co_u32_e32 v60, vcc, s4, v54
	s_mov_b32 s4, 0x30000
	s_nop 0
	v_addc_co_u32_e32 v61, vcc, 0, v55, vcc
	v_add_co_u32_e32 v16, vcc, s4, v16
	v_mov_b32_e32 v171, v2
	s_nop 0
	v_addc_co_u32_e32 v17, vcc, 0, v17, vcc
	v_add_co_u32_e32 v62, vcc, s4, v54
	global_load_dwordx4 v[118:121], v[8:9], off
	s_nop 0
	global_load_dwordx4 v[8:11], v[58:59], off
	global_load_dwordx4 v[134:137], v[12:13], off
	s_nop 0
	global_load_dwordx4 v[12:15], v[60:61], off
	v_addc_co_u32_e32 v63, vcc, 0, v55, vcc
	global_load_dwordx4 v[142:145], v[16:17], off
	global_load_dwordx4 v[50:53], v[62:63], off
	v_lshl_add_u64 v[16:17], v[56:57], 0, v[170:171]
	s_mov_b32 s4, 0x40000
	v_add_co_u32_e32 v56, vcc, s4, v16
	s_lshl_b32 s4, s90, 6
	s_nop 0
	v_addc_co_u32_e32 v57, vcc, 0, v17, vcc
	global_load_dwordx4 v[122:125], v[16:17], off
	global_load_dwordx4 v[126:129], v[56:57], off
	s_add_i32 s4, s4, 0
	s_add_i32 s4, s4, 0x15800
	v_or_b32_e32 v16, s38, v1
	v_mov_b32_e32 v17, s4
	s_movk_i32 s4, 0x210
	v_mad_u32_u24 v16, v16, s4, v17
	v_add_u32_e32 v169, v16, v157
	v_cvt_pk_bf16_f32 v16, v18, v19
	v_cvt_pk_bf16_f32 v17, v20, v21
	v_cvt_pk_bf16_f32 v56, v22, v23
	v_cvt_pk_bf16_f32 v57, v24, v25
	ds_write2_b64 v169, v[16:17], v[56:57] offset1:2
	v_cvt_pk_bf16_f32 v16, v26, v27
	v_cvt_pk_bf16_f32 v17, v28, v29
	v_cvt_pk_bf16_f32 v56, v30, v31
	v_cvt_pk_bf16_f32 v57, v32, v33
	ds_write2_b64 v169, v[16:17], v[56:57] offset0:4 offset1:6
	v_cvt_pk_bf16_f32 v16, v34, v35
	v_cvt_pk_bf16_f32 v17, v36, v37
	v_cvt_pk_bf16_f32 v56, v38, v39
	v_cvt_pk_bf16_f32 v57, v40, v41
	ds_write2_b64 v169, v[16:17], v[56:57] offset0:32 offset1:34
	v_mul_f32_e32 v56, v224, v159
	v_cmp_gt_f32_e32 vcc, s0, v56
	v_cvt_pk_bf16_f32 v16, v42, v43
	v_cvt_pk_bf16_f32 v17, v44, v45
	v_cndmask_b32_e32 v56, 0, v220, vcc
	v_fmac_f32_e32 v56, v224, v159
	v_exp_f32_e32 v65, v56
	v_cvt_pk_bf16_f32 v56, v46, v47
	v_cvt_pk_bf16_f32 v57, v48, v49
	ds_write2_b64 v169, v[16:17], v[56:57] offset0:36 offset1:38
	v_mul_f32_e32 v16, v224, v194
	v_mul_f32_e32 v3, 0x43000000, v224
	v_cndmask_b32_e32 v64, 0, v222, vcc
	v_cmp_gt_f32_e32 vcc, s0, v16
	s_lshl_b32 s62, s9, 9
	s_waitcnt vmcnt(0)
	ds_write_b128 v223, v[4:7] offset:34816
	ds_write_b128 v223, v[8:11] offset:43520
	ds_write_b128 v223, v[12:15] offset:52224
	ds_write_b128 v223, v[50:53] offset:60928
	global_load_dwordx4 v[130:133], v[54:55], off offset:256
	global_load_dwordx4 v[138:141], v[58:59], off offset:256
	global_load_dwordx4 v[146:149], v[60:61], off offset:256
	global_load_dwordx4 v[150:153], v[62:63], off offset:256
	v_cndmask_b32_e32 v16, 0, v222, vcc
	v_cndmask_b32_e32 v17, 0, v220, vcc
	v_cmp_gt_f32_e32 vcc, s0, v3
	s_lshl_b32 s55, s10, 7
	s_lshl_b32 s58, s9, 6
	v_cndmask_b32_e32 v3, 0, v220, vcc
	v_fmac_f32_e32 v3, 0x43000000, v224
	v_exp_f32_e32 v3, v3
	s_lshl_b32 s59, s10, 3
	s_lshl_b32 s66, s90, 5
	s_and_b64 s[4:5], vcc, exec
	s_cselect_b32 s4, 0xffffffc0, 0
	v_ldexp_f32 v176, v3, s4
	s_lshl_b32 s4, s8, 2
	s_lshr_b32 s5, 0x31002210, s4
	s_lshr_b32 s4, 0x33323210, s4
	s_cmpk_lt_u32 s57, 0x80
	s_cselect_b64 s[80:81], -1, 0
	s_cmpk_gt_u32 s57, 0x7f
	s_cselect_b64 s[72:73], -1, 0
	s_lshl_b32 s4, s4, 5
	s_lshl_b32 s5, s5, 5
	s_and_b32 s39, s4, 0x60
	s_lshl_b32 s4, s8, 4
	s_lshl_b32 s6, s8, 5
	s_and_b32 s5, s5, 0x60
	s_and_b32 s4, s4, 0x3fffffe0
	s_and_b32 s6, s6, 32
	s_cmpk_gt_u32 s57, 0xff
	s_cselect_b64 s[78:79], -1, 0
	s_cmpk_gt_u32 s57, 0x17f
	s_cselect_b64 s[76:77], -1, 0
	s_lshl_b64 s[60:61], s[52:53], 23
	v_fmac_f32_e32 v17, v224, v194
	s_or_b32 s60, s60, s62
	s_lshl_b64 s[68:69], s[52:53], 24
	v_exp_f32_e32 v17, v17
	s_add_u32 s62, s55, s54
	v_and_b32_e32 v8, 4, v156
	s_addc_u32 s63, 0, 0
	s_lshl_b32 s57, s56, 2
	v_or_b32_e32 v8, s5, v8
	s_or_b32 s57, s57, s59
	v_or_b32_e32 v4, s39, v1
	v_or_b32_e32 v7, s4, v201
	v_or_b32_e32 v9, 2, v8
	v_or_b32_e32 v10, 3, v8
	v_or_b32_e32 v11, 8, v8
	v_add_u32_e32 v57, s39, v199
	s_lshl_b64 s[64:65], s[90:91], 13
	s_or_b32 s57, s57, s58
	v_ldexp_f32 v174, v17, v16
	v_or_b32_e32 v3, s5, v1
	v_or_b32_e32 v5, s4, v1
	v_or_b32_e32 v6, s6, v1
	v_lshl_add_u32 v225, v7, 1, v196
	v_or_b32_e32 v7, s6, v201
	v_lshlrev_b32_e32 v227, 1, v8
	v_cmp_gt_u32_e64 s[4:5], v8, v4
	v_cmp_lt_u32_e64 s[6:7], v8, v4
	v_cmp_gt_u32_e64 s[8:9], v9, v4
	v_cmp_gt_u32_e64 s[10:11], v10, v4
	v_cmp_gt_u32_e64 s[12:13], v11, v4
	v_or_b32_e32 v12, 9, v8
	v_or_b32_e32 v13, 10, v8
	v_or_b32_e32 v14, 11, v8
	v_or_b32_e32 v15, 16, v8
	v_or_b32_e32 v16, 17, v8
	v_or_b32_e32 v17, 18, v8
	v_or_b32_e32 v50, 19, v8
	v_or_b32_e32 v51, 24, v8
	v_or_b32_e32 v52, 25, v8
	v_or_b32_e32 v53, 26, v8
	v_or_b32_e32 v54, 27, v8
	v_or_b32_e32 v56, s38, v201
	v_cmp_gt_u32_e64 s[38:39], v8, v57
	v_cmp_lt_u32_e64 s[40:41], v8, v57
	v_cmp_gt_u32_e64 s[42:43], v9, v57
	v_cmp_gt_u32_e64 s[44:45], v10, v57
	v_cmp_gt_u32_e64 s[46:47], v11, v57
	s_or_b64 s[62:63], s[62:63], s[68:69]
	s_lshl_b64 s[52:53], s[52:53], 20
	s_or_b32 s57, s64, s57
	v_or_b32_e32 v8, s66, v155
	v_or_b32_e32 v9, s66, v252
	v_or_b32_e32 v10, s66, v253
	v_or_b32_e32 v11, s66, v254
	s_add_u32 s64, s57, s52
	v_cvt_f32_u32_e32 v8, v8
	v_cvt_f32_u32_e32 v9, v9
	v_cvt_f32_u32_e32 v10, v10
	v_cvt_f32_u32_e32 v11, v11
	s_addc_u32 s65, s65, s53
	s_lshl_b32 s56, s56, 6
	s_lshl_b64 s[58:59], s[90:91], 17
	s_or_b32 s55, s56, s55
	v_cmp_gt_u32_e64 s[14:15], v12, v4
	v_cmp_gt_u32_e64 s[16:17], v13, v4
	v_cmp_gt_u32_e64 s[18:19], v14, v4
	v_cmp_gt_u32_e64 s[20:21], v15, v4
	v_cmp_gt_u32_e64 s[48:49], v12, v57
	v_cmp_gt_u32_e64 s[50:51], v13, v57
	v_cmp_gt_u32_e64 s[52:53], v14, v57
	s_add_u32 s56, s55, s54
	v_cmp_gt_u32_e64 s[54:55], v15, v57
	v_or_b32_e32 v12, s66, v198
	v_or_b32_e32 v13, s66, v206
	v_or_b32_e32 v14, s66, v207
	v_or_b32_e32 v15, s66, v208
	s_addc_u32 s57, 0, 0
	v_add_f32_e32 v228, 0xc2fe0000, v8
	v_add_f32_e32 v229, 0xc2fe0000, v9
	v_add_f32_e32 v230, 0xc2fe0000, v10
	v_add_f32_e32 v231, 0xc2fe0000, v11
	v_cvt_f32_u32_e32 v8, v12
	v_cvt_f32_u32_e32 v9, v13
	v_cvt_f32_u32_e32 v10, v14
	v_cvt_f32_u32_e32 v11, v15
	s_or_b64 s[56:57], s[56:57], s[58:59]
	s_add_u32 s68, s56, s68
	v_cmp_gt_u32_e64 s[22:23], v16, v4
	v_cmp_gt_u32_e64 s[24:25], v17, v4
	v_cmp_gt_u32_e64 s[26:27], v50, v4
	s_addc_u32 s69, s57, s69
	v_cmp_gt_u32_e64 s[56:57], v16, v57
	v_cmp_gt_u32_e64 s[58:59], v17, v57
	v_lshl_add_u64 v[178:179], s[60:61], 0, v[162:163]
	v_cmp_gt_u32_e64 s[60:61], v50, v57
	v_or_b32_e32 v16, s66, v209
	v_or_b32_e32 v17, s66, v210
	v_or_b32_e32 v50, s66, v211
	v_or_b32_e32 v59, s66, v212
	v_add_f32_e32 v232, 0xc2fe0000, v8
	v_add_f32_e32 v233, 0xc2fe0000, v9
	v_add_f32_e32 v234, 0xc2fe0000, v10
	v_add_f32_e32 v235, 0xc2fe0000, v11
	v_cvt_f32_u32_e32 v8, v16
	v_cvt_f32_u32_e32 v9, v17
	v_cvt_f32_u32_e32 v10, v50
	v_cvt_f32_u32_e32 v11, v59
	v_or_b32_e32 v60, s66, v213
	v_or_b32_e32 v61, s66, v214
	v_or_b32_e32 v62, s66, v215
	v_or_b32_e32 v63, s66, v216
	v_add_f32_e32 v236, 0xc2fe0000, v8
	v_add_f32_e32 v237, 0xc2fe0000, v9
	v_add_f32_e32 v238, 0xc2fe0000, v10
	v_add_f32_e32 v239, 0xc2fe0000, v11
	v_cvt_f32_u32_e32 v8, v60
	v_cvt_f32_u32_e32 v9, v61
	v_cvt_f32_u32_e32 v10, v62
	v_cvt_f32_u32_e32 v11, v63
	v_or_b32_e32 v55, s66, v1
	v_ldexp_f32 v172, v65, v64
	v_mul_u32_u24_e32 v3, 0x110, v3
	v_mad_u32_u24 v171, v4, s93, 0
	v_mul_lo_u32 v5, v5, s93
	v_mul_u32_u24_e32 v6, 0x210, v6
	v_lshlrev_b32_e32 v7, 1, v7
	v_cmp_gt_u32_e64 s[28:29], v51, v4
	v_cmp_gt_u32_e64 s[30:31], v52, v4
	v_cmp_gt_u32_e64 s[34:35], v53, v4
	v_cmp_gt_u32_e64 s[36:37], v54, v4
	v_add_u32_e32 v4, 0, v227
	v_mul_lo_u32 v55, v55, s93
	v_lshlrev_b32_e32 v56, 1, v56
	v_mul_u32_u24_e32 v58, 0x110, v57
	s_mov_b32 s85, 32
	v_add_u32_e32 v226, 0x8800, v225
	v_lshl_add_u64 v[180:181], s[62:63], 0, v[164:165]
	v_cmp_gt_u32_e64 s[62:63], v51, v57
	v_lshl_add_u64 v[182:183], s[64:65], 0, v[160:161]
	v_cmp_gt_u32_e64 s[64:65], v52, v57
	v_lshl_add_u64 v[184:185], s[68:69], 0, v[166:167]
	v_cmp_gt_u32_e64 s[66:67], v53, v57
	v_mov_b32_e32 v173, v172
	v_mov_b32_e32 v186, v172
	v_mov_b32_e32 v187, v172
	v_mov_b32_e32 v175, v174
	v_mov_b32_e32 v188, v174
	v_mov_b32_e32 v189, v174
	v_add_f32_e32 v240, 0xc2fe0000, v8
	v_add_f32_e32 v241, 0xc2fe0000, v9
	v_add_f32_e32 v242, 0xc2fe0000, v10
	v_add_f32_e32 v243, 0xc2fe0000, v11
	v_mov_b32_e32 v190, v176
	v_mov_b32_e32 v191, v176
	v_add_u32_e32 v244, v4, v58
	v_add_u32_e32 v245, v195, v3
	v_add_u32_e32 v246, v195, v5
	v_add_u32_e32 v247, v217, v6
	v_add_u32_e32 v248, v197, v7
	v_add_u32_e32 v249, v195, v55
	v_add_u32_e32 v250, v200, v56
	v_cmp_gt_u32_e64 s[68:69], v54, v57
	v_lshrrev_b32_e32 v155, 6, v0
	v_lshrrev_b32_e32 v156, 8, v0
	v_add_u32_e32 v155, v155, v156
	v_mov_b32_e32 v156, 0x1dc00
	v_lshl_add_u32 v155, v155, 11, v156
	v_and_b32_e32 v156, 31, v0
	v_lshl_add_u32 v154, v156, 1, v155
	v_and_b32_e32 v157, 32, v0
	v_lshl_add_u32 v154, v157, 3, v154
	v_and_b32_e32 v160, 63, v0
	v_lshl_add_u32 v155, v160, 4, v155
	v_lshrrev_b32_e32 v161, 2, v160
	v_lshlrev_b32_e32 v161, 12, v161
	v_and_b32_e32 v162, 3, v0
	v_lshl_add_u32 v161, v162, 4, v161
	v_lshlrev_b32_e32 v156, 1, v156
	v_lshl_add_u32 v156, v157, 9, v156
	v_sub_u32_e32 v156, v161, v156
	v_add_u32_e32 v156, 0xfa00000, v156
	v_mul_f32_e32 v198, v228, v224
	v_mul_f32_e32 v199, v229, v224
	v_mul_f32_e32 v200, v230, v224
	v_mul_f32_e32 v201, v231, v224
	v_mul_f32_e32 v206, v232, v224
	v_mul_f32_e32 v207, v233, v224
	v_mul_f32_e32 v208, v234, v224
	v_mul_f32_e32 v209, v235, v224
	v_mul_f32_e32 v210, v236, v224
	v_mul_f32_e32 v211, v237, v224
	v_mul_f32_e32 v212, v238, v224
	v_mul_f32_e32 v213, v239, v224
	v_mul_f32_e32 v214, v240, v224
	v_mul_f32_e32 v215, v241, v224
	v_mul_f32_e32 v216, v242, v224
	v_mul_f32_e32 v217, v243, v224
	v_exp_f32_e32 v198, v198
	v_exp_f32_e32 v199, v199
	v_exp_f32_e32 v200, v200
	v_exp_f32_e32 v201, v201
	v_exp_f32_e32 v206, v206
	v_exp_f32_e32 v207, v207
	v_exp_f32_e32 v208, v208
	v_exp_f32_e32 v209, v209
	v_exp_f32_e32 v210, v210
	v_exp_f32_e32 v211, v211
	v_exp_f32_e32 v212, v212
	v_exp_f32_e32 v213, v213
	v_exp_f32_e32 v214, v214
	v_exp_f32_e32 v215, v215
	v_exp_f32_e32 v216, v216
	v_exp_f32_e32 v217, v217
	v_mul_f32_e32 v228, v176, v198
	v_mul_f32_e32 v229, v176, v199
	v_mul_f32_e32 v230, v176, v200
	v_mul_f32_e32 v231, v176, v201
	v_mul_f32_e32 v232, v176, v206
	v_mul_f32_e32 v233, v176, v207
	v_mul_f32_e32 v234, v176, v208
	v_mul_f32_e32 v235, v176, v209
	v_mul_f32_e32 v236, v176, v210
	v_mul_f32_e32 v237, v176, v211
	v_mul_f32_e32 v238, v176, v212
	v_mul_f32_e32 v239, v176, v213
	v_mul_f32_e32 v240, v176, v214
	v_mul_f32_e32 v241, v176, v215
	v_mul_f32_e32 v242, v176, v216
	v_mul_f32_e32 v243, v176, v217
	s_branch .LBB0_593

.LBB0_612:
	v_lshl_add_u64 v[4:5], s[82:83], 0, v[184:185]
	v_mul_f32_e32 v8, v50, v228
	s_nop 5
	v_fmac_f32_e32 v8, v66, v198
	v_mul_f32_e32 v11, v51, v229
	v_fmac_f32_e32 v11, v67, v199
	v_mul_f32_e32 v13, v52, v230
	v_fmac_f32_e32 v13, v68, v200
	s_nop 0
	v_cvt_pk_bf16_f32 v10, v8, v11
	ds_write_b16 v154, v10
	ds_write_b16_d16_hi v154, v10 offset:64
	v_mul_f32_e32 v15, v53, v231
	v_fmac_f32_e32 v15, v69, v201
	s_nop 0
	v_cvt_pk_bf16_f32 v14, v13, v15
	ds_write_b16 v154, v14 offset:128
	ds_write_b16_d16_hi v154, v14 offset:192
	v_mul_f32_e32 v17, v54, v232
	v_fmac_f32_e32 v17, v70, v206
	v_mul_f32_e32 v51, v55, v233
	v_fmac_f32_e32 v51, v71, v207
	v_cvt_pk_bf16_f32 v50, v17, v51
	ds_write_b16 v154, v50 offset:512
	ds_write_b16_d16_hi v154, v50 offset:576
	v_mul_f32_e32 v53, v56, v234
	v_fmac_f32_e32 v53, v72, v208
	v_mul_f32_e32 v55, v57, v235
	v_fmac_f32_e32 v55, v73, v209
	s_nop 0
	v_cvt_pk_bf16_f32 v54, v53, v55
	ds_write_b16 v154, v54 offset:640
	ds_write_b16_d16_hi v154, v54 offset:704
	v_mul_f32_e32 v57, v58, v236
	v_fmac_f32_e32 v57, v74, v210
	s_nop 0
	v_mul_f32_e32 v59, v59, v237
	v_fmac_f32_e32 v59, v75, v211
	v_cvt_pk_bf16_f32 v58, v57, v59
	ds_write_b16 v154, v58 offset:1024
	ds_write_b16_d16_hi v154, v58 offset:1088
	v_mul_f32_e32 v60, v60, v238
	v_fmac_f32_e32 v60, v76, v212
	s_nop 0
	v_mul_f32_e32 v61, v61, v239
	v_fmac_f32_e32 v61, v77, v213
	v_cvt_pk_bf16_f32 v67, v60, v61
	ds_write_b16 v154, v67 offset:1152
	ds_write_b16_d16_hi v154, v67 offset:1216
	v_mul_f32_e32 v62, v62, v240
	v_fmac_f32_e32 v62, v78, v214
	s_nop 0
	v_mul_f32_e32 v63, v63, v241
	v_fmac_f32_e32 v63, v79, v215
	v_cvt_pk_bf16_f32 v69, v62, v63
	ds_write_b16 v154, v69 offset:1536
	ds_write_b16_d16_hi v154, v69 offset:1600
	v_mul_f32_e32 v7, v64, v242
	v_mul_f32_e32 v65, v65, v243
	v_fmac_f32_e32 v7, v80, v216
	v_fmac_f32_e32 v65, v81, v217
	v_cvt_pk_bf16_f32 v3, v7, v65
	ds_write_b16 v154, v3 offset:1664
	ds_write_b16_d16_hi v154, v3 offset:1728
	v_add_co_u32_e32 v194, vcc, v4, v156
	s_nop 1
	v_addc_co_u32_e32 v195, vcc, 0, v5, vcc
	v_add_co_u32_e32 v196, vcc, 0x10000, v194
	s_nop 1
	v_addc_co_u32_e32 v197, vcc, 0, v195, vcc
	s_waitcnt lgkmcnt(0)
	ds_read_b128 v[160:163], v155
	ds_read_b128 v[164:167], v155 offset:1024
	s_mov_b32 vcc_lo, 0xaaaaaaaa
	s_mov_b32 vcc_hi, 0xaaaaaaaa
	v_cndmask_b32_e32 v3, v8, v11, vcc
	v_cndmask_b32_e32 v4, v13, v15, vcc
	v_cndmask_b32_e32 v5, v17, v51, vcc
	v_cndmask_b32_e32 v6, v53, v55, vcc
	v_cndmask_b32_e32 v9, v57, v59, vcc
	v_cndmask_b32_e32 v10, v60, v61, vcc
	v_cndmask_b32_e32 v12, v62, v63, vcc
	v_cndmask_b32_e32 v14, v7, v65, vcc
	v_cndmask_b32_e32 v11, v11, v8, vcc
	v_cndmask_b32_e32 v15, v15, v13, vcc
	v_cndmask_b32_e32 v51, v51, v17, vcc
	v_cndmask_b32_e32 v55, v55, v53, vcc
	v_cndmask_b32_e32 v59, v59, v57, vcc
	v_cndmask_b32_e32 v61, v61, v60, vcc
	v_cndmask_b32_e32 v63, v63, v62, vcc
	v_cndmask_b32_e32 v65, v65, v7, vcc
	v_mul_f32_e32 v8, v3, v3
	v_mul_f32_e32 v13, v4, v4
	v_mul_f32_e32 v17, v5, v5
	v_mul_f32_e32 v53, v6, v6
	v_mul_f32_e32 v57, v9, v9
	v_mul_f32_e32 v60, v10, v10
	v_mul_f32_e32 v62, v12, v12
	v_mul_f32_e32 v7, v14, v14
	v_mul_f32_e32 v11, v11, v11
	v_mul_f32_e32 v15, v15, v15
	v_mul_f32_e32 v51, v51, v51
	v_mul_f32_e32 v55, v55, v55
	v_mul_f32_e32 v59, v59, v59
	v_mul_f32_e32 v61, v61, v61
	v_mul_f32_e32 v63, v63, v63
	v_mul_f32_e32 v65, v65, v65
	v_add_f32_dpp v8, v11, v8 quad_perm:[1,0,3,2] row_mask:0xf bank_mask:0xf
	v_add_f32_dpp v13, v15, v13 quad_perm:[1,0,3,2] row_mask:0xf bank_mask:0xf
	v_add_f32_dpp v17, v51, v17 quad_perm:[1,0,3,2] row_mask:0xf bank_mask:0xf
	v_add_f32_dpp v53, v55, v53 quad_perm:[1,0,3,2] row_mask:0xf bank_mask:0xf
	v_add_f32_dpp v57, v59, v57 quad_perm:[1,0,3,2] row_mask:0xf bank_mask:0xf
	v_add_f32_dpp v60, v61, v60 quad_perm:[1,0,3,2] row_mask:0xf bank_mask:0xf
	v_add_f32_dpp v62, v63, v62 quad_perm:[1,0,3,2] row_mask:0xf bank_mask:0xf
	v_add_f32_dpp v7, v65, v7 quad_perm:[1,0,3,2] row_mask:0xf bank_mask:0xf
	s_mov_b32 vcc_lo, 0xcccccccc
	s_mov_b32 vcc_hi, 0xcccccccc
	v_add_f32_dpp v8, v8, v8 quad_perm:[2,3,0,1] row_mask:0xf bank_mask:0xf
	v_add_f32_dpp v13, v13, v13 quad_perm:[2,3,0,1] row_mask:0xf bank_mask:0xf
	v_add_f32_dpp v17, v17, v17 quad_perm:[2,3,0,1] row_mask:0xf bank_mask:0xf
	v_add_f32_dpp v53, v53, v53 quad_perm:[2,3,0,1] row_mask:0xf bank_mask:0xf
	v_add_f32_dpp v57, v57, v57 quad_perm:[2,3,0,1] row_mask:0xf bank_mask:0xf
	v_add_f32_dpp v60, v60, v60 quad_perm:[2,3,0,1] row_mask:0xf bank_mask:0xf
	v_add_f32_dpp v62, v62, v62 quad_perm:[2,3,0,1] row_mask:0xf bank_mask:0xf
	v_add_f32_dpp v7, v7, v7 quad_perm:[2,3,0,1] row_mask:0xf bank_mask:0xf
	v_cndmask_b32_e32 v8, v8, v13, vcc
	v_cndmask_b32_e32 v17, v17, v53, vcc
	v_cndmask_b32_e32 v57, v57, v60, vcc
	v_cndmask_b32_e32 v62, v62, v7, vcc
	s_nop 1
	v_add_f32_dpp v16, v8, v8 row_shl:4 row_mask:0xf bank_mask:0x5
	v_add_f32_dpp v16, v17, v17 row_shr:4 row_mask:0xf bank_mask:0xa
	v_add_f32_dpp v50, v57, v57 row_shl:4 row_mask:0xf bank_mask:0x5
	v_add_f32_dpp v50, v62, v62 row_shr:4 row_mask:0xf bank_mask:0xa
	s_nop 1
	v_add_f32_dpp v12, v16, v16 row_shl:8 row_mask:0xf bank_mask:0x3
	v_add_f32_dpp v12, v50, v50 row_shr:8 row_mask:0xf bank_mask:0xc
	s_waitcnt lgkmcnt(0)
	global_store_dwordx4 v[194:195], v[160:163], off
	global_store_dwordx4 v[196:197], v[164:167], off
	v_mov_b32_e32 v14, v12
	v_and_b32_e32 v50, 15, v0
	v_lshrrev_b32_e32 v51, 2, v50
	v_and_b32_e32 v50, 3, v50
	v_lshlrev_b32_e32 v51, 11, v51
	v_lshl_or_b32 v50, v50, 8, v51
	v_add_u32_e32 v50, 0x200000, v50
	v_lshl_add_u64 v[4:5], s[82:83], 0, v[182:183]
	v_permlane16_swap_b32_e32 v12, v14
	v_add_co_u32_e32 v4, vcc, v4, v50
	v_add_f32_e32 v12, v12, v14
	s_nop 0
	v_addc_co_u32_e32 v5, vcc, 0, v5, vcc
	s_mov_b64 s[70:71], exec
	s_mov_b32 exec_lo, 0xffff
	s_mov_b32 exec_hi, 0xffff
	global_store_dword v[4:5], v12, off
	s_branch .LBB0_592
